# LN2 gamma/beta loads hoisted out of the row loop (registers), static setprio for waves 4-7; on top of v15
# speedup vs baseline: 1.0526x; 1.0090x over previous
; __device__ __forceinline__ void ln_phase(const Params& P, const float* g, const float* b, bf16_t* xb) {
;     const int lane = threadIdx.x & 63;
;     const int gw = blockIdx.x * 8 + (threadIdx.x >> 6), nw = gridDim.x * 8;
;     for (int row = gw; row < NTOK; row += nw) {
;         float* y = P.out + O_Y + (size_t)row * 2048;
;         float4 v[8]; float s = 0.f;
; #pragma unroll
;         for (int i = 0; i < 8; ++i) { v[i] = *(const float4*)(y + (i * 64 + lane) * 4); s += (v[i].x + v[i].y) + (v[i].z + v[i].w); }
;         s = halfsum32(s); s += __shfl_xor(s, 32);
;         const float mu = s * (1.0f / 2048.0f); float q = 0.f;
; #pragma unroll
;         for (int i = 0; i < 8; ++i) { v[i].x -= mu; v[i].y -= mu; v[i].z -= mu; v[i].w -= mu; q += (v[i].x * v[i].x + v[i].y * v[i].y) + (v[i].z * v[i].z + v[i].w * v[i].w); }
;         q = halfsum32(q); q += __shfl_xor(q, 32);
.LBB0_2835:
	s_or_b64 exec, exec, s[2:3]
	s_waitcnt lgkmcnt(0)
	s_barrier
	s_and_saveexec_b64 s[2:3], s[4:5]
	s_cbranch_execz .LBB0_2838
	v_and_b32_e32 v1, 64, v210
	v_xor_b32_e32 v0, 1, v210
	v_add_u32_e32 v1, 64, v1
	v_cmp_lt_i32_e32 vcc, v0, v1
	v_readlane_b32 s4, v252, 0
	v_readlane_b32 s5, v252, 1
	v_cndmask_b32_e32 v0, v210, v0, vcc
	v_lshlrev_b32_e32 v22, 2, v0
	v_xor_b32_e32 v0, 2, v210
	v_cmp_lt_i32_e32 vcc, v0, v1
	v_readlane_b32 s6, v252, 2
	v_readlane_b32 s7, v252, 3
	v_cndmask_b32_e32 v0, v210, v0, vcc
	v_lshlrev_b32_e32 v23, 2, v0
	v_xor_b32_e32 v0, 4, v210
	v_cmp_lt_i32_e32 vcc, v0, v1
	v_readlane_b32 s8, v252, 4
	v_readlane_b32 s9, v252, 5
	v_cndmask_b32_e32 v0, v210, v0, vcc
	v_lshlrev_b32_e32 v24, 2, v0
	v_xor_b32_e32 v0, 8, v210
	v_cmp_lt_i32_e32 vcc, v0, v1
	v_readlane_b32 s10, v252, 6
	v_readlane_b32 s11, v252, 7
	v_cndmask_b32_e32 v0, v210, v0, vcc
	v_lshlrev_b32_e32 v25, 2, v0
	v_xor_b32_e32 v0, 16, v210
	v_cmp_lt_i32_e32 vcc, v0, v1
	s_mov_b64 s[4:5], s[8:9]
	v_lshlrev_b64 v[20:21], 13, v[124:125]
	v_cndmask_b32_e32 v0, v210, v0, vcc
	v_lshlrev_b32_e32 v26, 2, v0
	v_xor_b32_e32 v0, 32, v210
	v_cmp_lt_i32_e32 vcc, v0, v1
	v_and_b32_e32 v18, 0x3f0, v144
	v_mov_b32_e32 v19, 0
	v_cndmask_b32_e32 v0, v210, v0, vcc
	s_mov_b64 s[6:7], s[10:11]
	v_lshl_or_b32 v20, v201, 4, v20
	v_lshlrev_b32_e32 v27, 2, v0
	v_lshl_add_u64 v[0:1], s[4:5], 0, v[18:19]
	v_lshl_add_u64 v[2:3], s[6:7], 0, v[18:19]
	v_or_b32_e32 v6, 0x1000, v18
	v_mov_b32_e32 v7, v19
	v_or_b32_e32 v10, 0x1400, v18
	v_mov_b32_e32 v11, v19
	v_or_b32_e32 v14, 0x1800, v18
	v_mov_b32_e32 v15, v19
	v_or_b32_e32 v18, 0x1c00, v18
	v_lshl_add_u64 v[20:21], s[88:89], 0, v[20:21]
	s_mov_b64 s[2:3], 0x1000
	s_ashr_i32 s1, s0, 31
	v_lshl_add_u64 v[4:5], s[4:5], 0, v[6:7]
	v_lshl_add_u64 v[6:7], s[6:7], 0, v[6:7]
	v_lshl_add_u64 v[8:9], s[4:5], 0, v[10:11]
	v_lshl_add_u64 v[10:11], s[6:7], 0, v[10:11]
	v_lshl_add_u64 v[12:13], s[4:5], 0, v[14:15]
	v_lshl_add_u64 v[14:15], s[6:7], 0, v[14:15]
	v_lshl_add_u64 v[16:17], s[4:5], 0, v[18:19]
	v_lshl_add_u64 v[18:19], s[6:7], 0, v[18:19]
	v_lshl_add_u64 v[20:21], v[20:21], 0, s[2:3]
	s_lshl_b64 s[2:3], s[0:1], 13
	s_mov_b64 s[4:5], 0
	v_mov_b32_e32 v28, 0x3727c5ac
	s_mov_b32 s1, 0x800000
	s_movk_i32 s6, 0x41ff
	global_load_dwordx4 v[150:153], v[0:1], off
	global_load_dwordx4 v[154:157], v[2:3], off
	global_load_dwordx4 v[158:161], v[0:1], off offset:1024
	global_load_dwordx4 v[162:165], v[2:3], off offset:1024
	global_load_dwordx4 v[166:169], v[0:1], off offset:2048
	global_load_dwordx4 v[170:173], v[2:3], off offset:2048
	global_load_dwordx4 v[174:177], v[0:1], off offset:3072
	global_load_dwordx4 v[178:181], v[2:3], off offset:3072
	global_load_dwordx4 v[182:185], v[4:5], off
	global_load_dwordx4 v[186:189], v[6:7], off
	global_load_dwordx4 v[190:193], v[8:9], off
	global_load_dwordx4 v[194:197], v[10:11], off
	global_load_dwordx4 v[198:201], v[12:13], off
	global_load_dwordx4 v[202:205], v[14:15], off
	global_load_dwordx4 v[206:209], v[16:17], off
	global_load_dwordx4 v[210:213], v[18:19], off
	s_waitcnt vmcnt(0)
.LBB0_2837:
	global_load_dwordx4 v[30:33], v[20:21], off offset:-4096
	global_load_dwordx4 v[34:37], v[20:21], off offset:-3072
	global_load_dwordx4 v[38:41], v[20:21], off offset:-2048
	global_load_dwordx4 v[42:45], v[20:21], off offset:-1024
	global_load_dwordx4 v[46:49], v[20:21], off
	global_load_dwordx4 v[50:53], v[20:21], off offset:1024
	global_load_dwordx4 v[54:57], v[20:21], off offset:2048
	global_load_dwordx4 v[58:61], v[20:21], off offset:3072
	v_add_u32_e32 v124, s0, v124
	s_waitcnt vmcnt(7)
	v_mov_b32_e32 v62, v30
	s_waitcnt vmcnt(6)
	v_mov_b32_e32 v63, v34
	v_mov_b32_e32 v64, v31
	v_mov_b32_e32 v65, v35
	v_mov_b32_e32 v66, v32
	v_mov_b32_e32 v67, v36
	v_mov_b32_e32 v68, v33
	v_mov_b32_e32 v69, v37
	s_waitcnt vmcnt(5)
	v_mov_b32_e32 v70, v38
	v_mov_b32_e32 v71, v40
	v_mov_b32_e32 v72, v39
	v_mov_b32_e32 v73, v41
	v_pk_add_f32 v[62:63], v[62:63], v[64:65]
	v_pk_add_f32 v[64:65], v[66:67], v[68:69]
	s_waitcnt vmcnt(4)
	v_mov_b32_e32 v74, v43
	v_mov_b32_e32 v76, v45
	s_waitcnt vmcnt(3)
	v_mov_b32_e32 v75, v46
	v_pk_add_f32 v[66:67], v[70:71], v[72:73]
	v_pk_add_f32 v[62:63], v[62:63], v[64:65]
	v_pk_add_f32 v[68:69], v[42:43], v[74:75]
	v_pk_add_f32 v[70:71], v[44:45], v[76:77]
	v_pk_add_f32 v[64:65], v[66:67], v[66:67] op_sel:[0,1] op_sel_hi:[1,0]
	v_add_f32_e32 v29, 0, v62
	v_mov_b32_e32 v69, v48
	v_mov_b32_e32 v71, v49
	v_mov_b32_e32 v65, v47
	v_add_f32_e32 v74, v29, v63
	s_waitcnt vmcnt(2)
	v_mov_b32_e32 v78, v50
	v_mov_b32_e32 v79, v52
	v_mov_b32_e32 v80, v51
	v_mov_b32_e32 v81, v53
	v_pk_add_f32 v[68:69], v[68:69], v[70:71]
	v_pk_add_f32 v[62:63], v[74:75], v[64:65]
	s_waitcnt vmcnt(1)
	v_mov_b32_e32 v82, v55
	v_mov_b32_e32 v84, v57
	v_pk_add_f32 v[72:73], v[78:79], v[80:81]
	v_pk_add_f32 v[62:63], v[62:63], v[68:69]
	v_pk_add_f32 v[76:77], v[54:55], v[82:83]
	v_pk_add_f32 v[78:79], v[56:57], v[84:85]
	v_pk_add_f32 v[66:67], v[72:73], v[72:73] op_sel:[0,1] op_sel_hi:[1,0]
	v_pk_add_f32 v[62:63], v[62:63], v[62:63] op_sel:[0,1] op_sel_hi:[1,0]
	s_waitcnt vmcnt(0)
	v_mov_b32_e32 v77, v60
	v_mov_b32_e32 v79, v61
	v_mov_b32_e32 v67, v59
	v_mov_b32_e32 v63, v58
	v_pk_add_f32 v[70:71], v[76:77], v[78:79]
	v_pk_add_f32 v[62:63], v[62:63], v[66:67]
	s_nop 0
	v_pk_add_f32 v[62:63], v[62:63], v[70:71]
	s_nop 0
	v_add_f32_e32 v29, v62, v63
	ds_bpermute_b32 v62, v22, v29
	s_waitcnt lgkmcnt(0)
	v_add_f32_e32 v29, v29, v62
	ds_bpermute_b32 v62, v23, v29
	s_waitcnt lgkmcnt(0)
	v_add_f32_e32 v29, v29, v62
	ds_bpermute_b32 v62, v24, v29
	s_waitcnt lgkmcnt(0)
	v_add_f32_e32 v29, v29, v62
	ds_bpermute_b32 v62, v25, v29
	s_waitcnt lgkmcnt(0)
; __device__ __forceinline__ void ln_phase(const Params& P, const float* g, const float* b, bf16_t* xb) {
;     ...
;         const float mu = s * (1.0f / 2048.0f); float q = 0.f;
; #pragma unroll
;         for (int i = 0; i < 8; ++i) { v[i].x -= mu; v[i].y -= mu; v[i].z -= mu; v[i].w -= mu; q += (v[i].x * v[i].x + v[i].y * v[i].y) + (v[i].z * v[i].z + v[i].w * v[i].w); }
;         q = halfsum32(q); q += __shfl_xor(q, 32);
;         const float rstd = rsqrtf(q * (1.0f / 2048.0f) + 1e-5f);
; #pragma unroll
;         for (int i = 0; i < 8; ++i) { const int c = (i * 64 + lane) * 4; const float4 gg = *(const float4*)(g + c), bb = *(const float4*)(b + c);
	v_add_f32_e32 v29, v29, v62
	ds_bpermute_b32 v62, v26, v29
	s_waitcnt lgkmcnt(0)
	v_add_f32_e32 v29, v29, v62
	s_nop 1
	v_mov_b64_e32 v[62:63], v[150:151]
	v_mov_b64_e32 v[64:65], v[152:153]
	s_nop 1
	v_mov_b64_e32 v[66:67], v[154:155]
	v_mov_b64_e32 v[68:69], v[156:157]
	ds_bpermute_b32 v70, v27, v29
	s_waitcnt lgkmcnt(0)
	v_add_f32_e32 v29, v29, v70
	v_mul_f32_e32 v70, 0x3a000000, v29
	v_pk_add_f32 v[30:31], v[30:31], v[70:71] op_sel_hi:[1,0] neg_lo:[0,1] neg_hi:[0,1]
	v_pk_add_f32 v[32:33], v[32:33], v[70:71] op_sel_hi:[1,0] neg_lo:[0,1] neg_hi:[0,1]
	v_pk_add_f32 v[72:73], v[34:35], v[70:71] op_sel_hi:[1,0] neg_lo:[0,1] neg_hi:[0,1]
	v_pk_add_f32 v[74:75], v[36:37], v[70:71] op_sel_hi:[1,0] neg_lo:[0,1] neg_hi:[0,1]
	v_pk_add_f32 v[38:39], v[38:39], v[70:71] op_sel_hi:[1,0] neg_lo:[0,1] neg_hi:[0,1]
	v_pk_add_f32 v[40:41], v[40:41], v[70:71] op_sel_hi:[1,0] neg_lo:[0,1] neg_hi:[0,1]
	v_mov_b32_e32 v36, v31
	v_mov_b32_e32 v37, v73
	v_mov_b32_e32 v76, v33
	v_mov_b32_e32 v77, v75
	v_pk_add_f32 v[42:43], v[42:43], v[70:71] op_sel_hi:[1,0] neg_lo:[0,1] neg_hi:[0,1]
	v_pk_add_f32 v[44:45], v[44:45], v[70:71] op_sel_hi:[1,0] neg_lo:[0,1] neg_hi:[0,1]
	v_pk_add_f32 v[46:47], v[46:47], v[70:71] op_sel_hi:[1,0] neg_lo:[0,1] neg_hi:[0,1]
	v_pk_add_f32 v[48:49], v[48:49], v[70:71] op_sel_hi:[1,0] neg_lo:[0,1] neg_hi:[0,1]
	v_pk_add_f32 v[50:51], v[50:51], v[70:71] op_sel_hi:[1,0] neg_lo:[0,1] neg_hi:[0,1]
	v_pk_add_f32 v[52:53], v[52:53], v[70:71] op_sel_hi:[1,0] neg_lo:[0,1] neg_hi:[0,1]
	v_pk_add_f32 v[54:55], v[54:55], v[70:71] op_sel_hi:[1,0] neg_lo:[0,1] neg_hi:[0,1]
	v_pk_add_f32 v[56:57], v[56:57], v[70:71] op_sel_hi:[1,0] neg_lo:[0,1] neg_hi:[0,1]
	v_pk_add_f32 v[58:59], v[58:59], v[70:71] op_sel_hi:[1,0] neg_lo:[0,1] neg_hi:[0,1]
	v_pk_add_f32 v[60:61], v[60:61], v[70:71] op_sel_hi:[1,0] neg_lo:[0,1] neg_hi:[0,1]
	v_mov_b32_e32 v34, v30
	v_mov_b32_e32 v35, v72
	v_mov_b32_e32 v70, v32
	v_mov_b32_e32 v71, v74
	v_mov_b32_e32 v80, v39
	v_mov_b32_e32 v81, v41
	v_pk_mul_f32 v[36:37], v[36:37], v[36:37]
	v_pk_mul_f32 v[76:77], v[76:77], v[76:77]
	v_mov_b32_e32 v78, v38
	v_mov_b32_e32 v79, v40
	v_pk_mul_f32 v[80:81], v[80:81], v[80:81]
	v_pk_fma_f32 v[34:35], v[34:35], v[34:35], v[36:37]
	v_pk_fma_f32 v[36:37], v[70:71], v[70:71], v[76:77]
	v_mul_f32_e32 v82, v42, v42
	v_mul_f32_e32 v84, v44, v44
	v_pk_fma_f32 v[70:71], v[78:79], v[78:79], v[80:81]
	v_pk_add_f32 v[34:35], v[34:35], v[36:37]
	v_pk_mul_f32 v[86:87], v[46:47], v[46:47]
	v_pk_mul_f32 v[88:89], v[48:49], v[48:49]
	v_pk_fma_f32 v[82:83], v[42:43], v[42:43], v[82:83] op_sel_hi:[1,1,0]
	v_pk_fma_f32 v[84:85], v[44:45], v[44:45], v[84:85] op_sel_hi:[1,1,0]
	v_pk_add_f32 v[36:37], v[70:71], v[70:71] op_sel_hi:[0,1]
	v_pk_add_f32 v[34:35], v[34:35], v[34:35] op_sel_hi:[0,1]
	v_mov_b32_e32 v92, v51
	v_mov_b32_e32 v93, v53
	v_mov_b32_e32 v82, v86
	v_mov_b32_e32 v84, v87
	v_mov_b32_e32 v36, v88
	v_mov_b32_e32 v34, v89
	v_mov_b32_e32 v90, v50
	v_mov_b32_e32 v91, v52
	v_pk_mul_f32 v[92:93], v[92:93], v[92:93]
	v_pk_add_f32 v[70:71], v[82:83], v[84:85]
	v_pk_add_f32 v[34:35], v[36:37], v[34:35]
	v_mul_f32_e32 v94, v54, v54
	v_mul_f32_e32 v96, v56, v56
	v_pk_fma_f32 v[76:77], v[90:91], v[90:91], v[92:93]
	v_pk_add_f32 v[34:35], v[70:71], v[34:35]
	v_pk_mul_f32 v[98:99], v[58:59], v[58:59]
	v_pk_mul_f32 v[100:101], v[60:61], v[60:61]
	v_pk_fma_f32 v[94:95], v[54:55], v[54:55], v[94:95] op_sel_hi:[1,1,0]
	v_pk_fma_f32 v[96:97], v[56:57], v[56:57], v[96:97] op_sel_hi:[1,1,0]
	v_pk_add_f32 v[76:77], v[76:77], v[76:77] op_sel_hi:[0,1]
	v_pk_add_f32 v[34:35], v[34:35], v[34:35] op_sel_hi:[0,1]
	v_mov_b32_e32 v94, v98
	v_mov_b32_e32 v96, v99
	v_mov_b32_e32 v76, v100
	v_mov_b32_e32 v34, v101
	v_pk_add_f32 v[78:79], v[94:95], v[96:97]
	v_pk_add_f32 v[34:35], v[76:77], v[34:35]
	s_nop 0
	v_pk_add_f32 v[34:35], v[78:79], v[34:35]
	s_nop 0
	v_add_f32_e32 v29, v34, v35
	ds_bpermute_b32 v34, v22, v29
	s_waitcnt lgkmcnt(0)
	v_add_f32_e32 v29, v29, v34
	ds_bpermute_b32 v34, v23, v29
	s_waitcnt lgkmcnt(0)
	v_add_f32_e32 v29, v29, v34
	ds_bpermute_b32 v34, v24, v29
	s_waitcnt lgkmcnt(0)
; __device__ __forceinline__ void ln_phase(const Params& P, const float* g, const float* b, bf16_t* xb) {
;     ...
;         q = halfsum32(q); q += __shfl_xor(q, 32);
;         const float rstd = rsqrtf(q * (1.0f / 2048.0f) + 1e-5f);
; #pragma unroll
;         for (int i = 0; i < 8; ++i) { const int c = (i * 64 + lane) * 4; const float4 gg = *(const float4*)(g + c), bb = *(const float4*)(b + c);
;             float4 o; o.x = v[i].x * rstd * gg.x + bb.x; o.y = v[i].y * rstd * gg.y + bb.y; o.z = v[i].z * rstd * gg.z + bb.z; o.w = v[i].w * rstd * gg.w + bb.w;
;             *(float4*)(y + c) = o;
	v_add_f32_e32 v29, v29, v34
	ds_bpermute_b32 v34, v25, v29
	s_waitcnt lgkmcnt(0)
	v_add_f32_e32 v29, v29, v34
	ds_bpermute_b32 v34, v26, v29
	s_waitcnt lgkmcnt(0)
	v_add_f32_e32 v29, v29, v34
	ds_bpermute_b32 v34, v27, v29
	s_waitcnt lgkmcnt(0)
	v_add_f32_e32 v29, v29, v34
	v_fmamk_f32 v29, v29, 0x3a000000, v28
	v_mul_f32_e32 v34, 0x4b800000, v29
	v_cmp_gt_f32_e32 vcc, s1, v29
	s_nop 1
	v_cndmask_b32_e32 v29, v29, v34, vcc
	v_rsq_f32_e32 v29, v29
	s_nop 0
	v_mul_f32_e32 v34, 0x45800000, v29
	v_cndmask_b32_e32 v70, v29, v34, vcc
	v_pk_mul_f32 v[30:31], v[30:31], v[70:71] op_sel_hi:[1,0]
	v_pk_mul_f32 v[32:33], v[32:33], v[70:71] op_sel_hi:[1,0]
	v_pk_fma_f32 v[30:31], v[62:63], v[30:31], v[66:67]
	v_pk_fma_f32 v[32:33], v[64:65], v[32:33], v[68:69]
	global_store_dwordx4 v[20:21], v[30:33], off offset:-4096
	s_nop 1
	v_mov_b64_e32 v[30:31], v[158:159]
	v_mov_b64_e32 v[32:33], v[160:161]
	s_nop 0
	s_nop 1
	v_mov_b64_e32 v[34:35], v[162:163]
	v_mov_b64_e32 v[36:37], v[164:165]
	v_pk_mul_f32 v[62:63], v[72:73], v[70:71] op_sel_hi:[1,0]
	v_pk_mul_f32 v[64:65], v[74:75], v[70:71] op_sel_hi:[1,0]
	v_pk_mul_f32 v[38:39], v[38:39], v[70:71] op_sel_hi:[1,0]
	v_pk_mul_f32 v[40:41], v[40:41], v[70:71] op_sel_hi:[1,0]
	v_cmp_lt_i32_e32 vcc, s6, v124
	s_or_b64 s[4:5], vcc, s[4:5]
	v_pk_fma_f32 v[30:31], v[30:31], v[62:63], v[34:35]
	v_pk_fma_f32 v[32:33], v[32:33], v[64:65], v[36:37]
	global_store_dwordx4 v[20:21], v[30:33], off offset:-3072
	s_nop 1
	v_mov_b64_e32 v[30:31], v[166:167]
	v_mov_b64_e32 v[32:33], v[168:169]
	s_nop 0
	s_nop 1
	v_mov_b64_e32 v[34:35], v[170:171]
	v_mov_b64_e32 v[36:37], v[172:173]
	v_pk_fma_f32 v[30:31], v[38:39], v[30:31], v[34:35]
	v_pk_fma_f32 v[32:33], v[40:41], v[32:33], v[36:37]
	global_store_dwordx4 v[20:21], v[30:33], off offset:-2048
	s_nop 1
	v_mov_b64_e32 v[30:31], v[174:175]
	v_mov_b64_e32 v[32:33], v[176:177]
	s_nop 0
	s_nop 1
	v_mov_b64_e32 v[34:35], v[178:179]
	v_mov_b64_e32 v[36:37], v[180:181]
	v_pk_mul_f32 v[38:39], v[42:43], v[70:71] op_sel_hi:[1,0]
	v_pk_mul_f32 v[40:41], v[44:45], v[70:71] op_sel_hi:[1,0]
	v_pk_fma_f32 v[30:31], v[38:39], v[30:31], v[34:35]
	v_pk_fma_f32 v[32:33], v[40:41], v[32:33], v[36:37]
	global_store_dwordx4 v[20:21], v[30:33], off offset:-1024
	s_nop 1
	v_mov_b64_e32 v[30:31], v[182:183]
	v_mov_b64_e32 v[32:33], v[184:185]
	s_nop 0
	s_nop 1
	v_mov_b64_e32 v[34:35], v[186:187]
	v_mov_b64_e32 v[36:37], v[188:189]
	v_pk_mul_f32 v[38:39], v[46:47], v[70:71] op_sel_hi:[1,0]
	v_pk_mul_f32 v[40:41], v[48:49], v[70:71] op_sel_hi:[1,0]
	v_pk_fma_f32 v[30:31], v[38:39], v[30:31], v[34:35]
	v_pk_fma_f32 v[32:33], v[40:41], v[32:33], v[36:37]
	global_store_dwordx4 v[20:21], v[30:33], off
	s_nop 1
	v_mov_b64_e32 v[30:31], v[190:191]
	v_mov_b64_e32 v[32:33], v[192:193]
	s_nop 0
	s_nop 1
	v_mov_b64_e32 v[34:35], v[194:195]
	v_mov_b64_e32 v[36:37], v[196:197]
	v_pk_mul_f32 v[38:39], v[50:51], v[70:71] op_sel_hi:[1,0]
	v_pk_mul_f32 v[40:41], v[52:53], v[70:71] op_sel_hi:[1,0]
	v_pk_fma_f32 v[30:31], v[38:39], v[30:31], v[34:35]
	v_pk_fma_f32 v[32:33], v[40:41], v[32:33], v[36:37]
	global_store_dwordx4 v[20:21], v[30:33], off offset:1024
	s_nop 1
	v_mov_b64_e32 v[30:31], v[198:199]
	v_mov_b64_e32 v[32:33], v[200:201]
	s_nop 0
	s_nop 1
	v_mov_b64_e32 v[34:35], v[202:203]
	v_mov_b64_e32 v[36:37], v[204:205]
	v_pk_mul_f32 v[38:39], v[54:55], v[70:71] op_sel_hi:[1,0]
	v_pk_mul_f32 v[40:41], v[56:57], v[70:71] op_sel_hi:[1,0]
	v_pk_fma_f32 v[30:31], v[38:39], v[30:31], v[34:35]
	v_pk_fma_f32 v[32:33], v[40:41], v[32:33], v[36:37]
	global_store_dwordx4 v[20:21], v[30:33], off offset:2048
	s_nop 1
	v_mov_b64_e32 v[30:31], v[206:207]
	v_mov_b64_e32 v[32:33], v[208:209]
	s_nop 0
	s_nop 1
	v_mov_b64_e32 v[34:35], v[210:211]
	v_mov_b64_e32 v[36:37], v[212:213]
	v_pk_mul_f32 v[38:39], v[58:59], v[70:71] op_sel_hi:[1,0]
	v_pk_mul_f32 v[40:41], v[60:61], v[70:71] op_sel_hi:[1,0]
	v_pk_fma_f32 v[30:31], v[38:39], v[30:31], v[34:35]
	v_pk_fma_f32 v[32:33], v[40:41], v[32:33], v[36:37]
	global_store_dwordx4 v[20:21], v[30:33], off offset:3072
	v_lshl_add_u64 v[20:21], v[20:21], 0, s[2:3]
	s_andn2_b64 exec, exec, s[4:5]
	s_cbranch_execnz .LBB0_2837
